# P7 group stagger shortened to 2 x s_sleep 127 (about 7 us); otherwise v84 (group-local syncs, write-through 16-byte stores in P1/P6/P7/P9)
# speedup vs baseline: 1.0117x; 1.0023x over previous
.LBB0_486:
	s_or_b64 exec, exec, s[4:5]
	s_bitcmp1_b32 s2, 0
	s_cbranch_scc0 .Lstg_skip
	s_movk_i32 s74, 2
